# CW10: counted-wait variant with the staging pieces after PV MFMAs 1,3,5,7 (read-first ordering, relaxed lgkmcnt)
# speedup vs baseline: 1.0079x; 1.0057x over previous
.LBB0_672:
	s_nop 7
	v_exp_f32_e32 v2, v48
	v_exp_f32_e32 v3, v49
	v_exp_f32_e32 v4, v50
	v_exp_f32_e32 v5, v51
	v_add_f32_e32 v0, 0, v2
	v_exp_f32_e32 v6, v52
	v_add_f32_e32 v0, v3, v0
	v_exp_f32_e32 v7, v53
	v_add_f32_e32 v0, v4, v0
	v_exp_f32_e32 v8, v54
	v_add_f32_e32 v0, v5, v0
	v_exp_f32_e32 v9, v55
	v_add_f32_e32 v0, v6, v0
	v_add_f32_e32 v0, v7, v0
	v_exp_f32_e32 v50, v60
	v_exp_f32_e32 v60, v70
	v_add3_u32 v70, s6, v143, v145
	v_add_f32_e32 v0, v8, v0
	v_exp_f32_e32 v51, v61
	v_exp_f32_e32 v61, v71
	v_add_u32_e32 v71, 0x2000, v70
	v_add_f32_e32 v0, v9, v0
	v_cvt_pk_bf16_f32 v2, v2, v3
	v_cvt_pk_bf16_f32 v3, v4, v5
	v_cvt_pk_bf16_f32 v4, v6, v7
	v_cvt_pk_bf16_f32 v5, v8, v9
	ds_read2_b64 v[6:9], v71 offset0:128 offset1:130
	ds_read2_b64 v[10:13], v71 offset0:132 offset1:134
	v_add_u32_e32 v70, 0x3000, v70
	s_waitcnt lgkmcnt(1)
	v_mfma_f32_32x32x16_bf16 v[32:47], v[6:9], v[2:5], v[32:47]
	ds_read2_b64 v[6:9], v70 offset0:160 offset1:162
	s_mul_i32 s16, s4, 0x4a00
	v_or_b32_e32 v252, s16, v125
	v_add_u32_e32 v253, v252, v137
	s_waitcnt vmcnt(3)
	ds_write_b128 v253, v[100:103]
	global_load_dwordx4 v[100:103], v228, s[10:11]
	v_exp_f32_e32 v14, v56
	v_exp_f32_e32 v15, v57
	v_exp_f32_e32 v48, v58
	v_exp_f32_e32 v49, v59
	v_exp_f32_e32 v52, v62
	v_exp_f32_e32 v53, v63
	s_waitcnt lgkmcnt(1)
	v_mfma_f32_32x32x16_bf16 v[16:31], v[6:9], v[2:5], v[16:31]
	ds_read2_b64 v[6:9], v70 offset0:164 offset1:166
	v_cvt_pk_bf16_f32 v2, v14, v15
	v_cvt_pk_bf16_f32 v3, v48, v49
	v_cvt_pk_bf16_f32 v4, v50, v51
	v_cvt_pk_bf16_f32 v5, v52, v53
	v_exp_f32_e32 v54, v64
	v_exp_f32_e32 v55, v65
	s_waitcnt lgkmcnt(0)
	v_mfma_f32_32x32x16_bf16 v[16:31], v[6:9], v[2:5], v[16:31]
	ds_read2_b64 v[6:9], v71 offset0:136 offset1:138
	v_add3_u32 v253, v252, v138, s33
	s_waitcnt vmcnt(2)
	ds_write2_b64 v253, v[104:105], v[106:107] offset1:1
	global_load_dwordx4 v[104:107], v230, s[22:23]
	v_exp_f32_e32 v56, v66
	v_exp_f32_e32 v57, v67
	v_exp_f32_e32 v58, v68
	v_exp_f32_e32 v59, v69
	v_add_f32_e32 v0, v14, v0
	v_add_f32_e32 v0, v15, v0
	v_mfma_f32_32x32x16_bf16 v[32:47], v[10:13], v[2:5], v[32:47]
	v_cvt_pk_bf16_f32 v2, v54, v55
	v_cvt_pk_bf16_f32 v3, v56, v57
	v_cvt_pk_bf16_f32 v4, v58, v59
	v_cvt_pk_bf16_f32 v5, v60, v61
	v_add_f32_e32 v0, v48, v0
	v_add_f32_e32 v0, v49, v0
	v_exp_f32_e32 v62, v72
	s_waitcnt lgkmcnt(1)
	v_mfma_f32_32x32x16_bf16 v[32:47], v[6:9], v[2:5], v[32:47]
	ds_read2_b64 v[6:9], v70 offset0:168 offset1:170
	v_add_u32_e32 v253, v252, v139
	s_waitcnt vmcnt(3)
	ds_write_b128 v253, v[108:111]
	global_load_dwordx4 v[108:111], v229, s[10:11]
	v_exp_f32_e32 v63, v73
	v_exp_f32_e32 v64, v74
	v_exp_f32_e32 v65, v75
	v_exp_f32_e32 v66, v76
	v_exp_f32_e32 v67, v77
	v_exp_f32_e32 v68, v78
	s_waitcnt lgkmcnt(1)
	v_mfma_f32_32x32x16_bf16 v[16:31], v[6:9], v[2:5], v[16:31]
	ds_read2_b64 v[6:9], v71 offset0:140 offset1:142
	v_exp_f32_e32 v69, v79
	v_add_f32_e32 v0, v50, v0
	v_add_f32_e32 v0, v51, v0
	v_add_f32_e32 v0, v52, v0
	v_add_f32_e32 v0, v53, v0
	v_cvt_pk_bf16_f32 v2, v62, v63
	v_cvt_pk_bf16_f32 v3, v64, v65
	v_cvt_pk_bf16_f32 v4, v66, v67
	v_cvt_pk_bf16_f32 v5, v68, v69
	v_add_f32_e32 v0, v54, v0
	v_add_f32_e32 v0, v55, v0
	s_waitcnt lgkmcnt(0)
	v_mfma_f32_32x32x16_bf16 v[32:47], v[6:9], v[2:5], v[32:47]
	ds_read2_b64 v[6:9], v70 offset0:172 offset1:174
	v_add3_u32 v253, v252, v140, s33
	s_waitcnt vmcnt(3)
	ds_write2_b64 v253, v[112:113], v[114:115] offset1:1
	global_load_dwordx4 v[112:115], v231, s[22:23]
	s_add_u32 s10, s10, 0x2000
	s_addc_u32 s11, s11, 0
	s_add_u32 s22, s22, 0x80
	s_addc_u32 s23, s23, 0
	v_add_f32_e32 v0, v56, v0
	v_add_f32_e32 v0, v57, v0
	v_add_f32_e32 v0, v58, v0
	v_add_f32_e32 v0, v59, v0
	v_add_f32_e32 v0, v60, v0
	v_add_f32_e32 v0, v61, v0
	v_add_f32_e32 v0, v62, v0
	v_add_f32_e32 v0, v63, v0
	s_waitcnt lgkmcnt(1)
	v_mfma_f32_32x32x16_bf16 v[16:31], v[6:9], v[2:5], v[16:31]
	s_and_saveexec_b64 s[0:1], s[38:39]
	s_cbranch_execz .Ld5f_noga
	s_waitcnt vmcnt(4)
	v_xor_b32_e32 v239, 0x80000000, v99
	v_xor_b32_e32 v238, 0x80000000, v98
	v_xor_b32_e32 v237, 0x80000000, v97
	v_xor_b32_e32 v236, 0x80000000, v96
	v_add_u32_e32 v253, s16, v119
	ds_write_b128 v253, v[236:239] offset:18432
	global_load_dwordx4 v[96:99], v228, s[24:25]

.LBB0_705:
	s_nop 7
	v_exp_f32_e32 v2, v80
	v_exp_f32_e32 v3, v81
	v_exp_f32_e32 v4, v82
	v_exp_f32_e32 v5, v83
	v_add_f32_e32 v0, 0, v2
	v_exp_f32_e32 v6, v84
	v_add_f32_e32 v0, v3, v0
	v_exp_f32_e32 v7, v85
	v_add_f32_e32 v0, v4, v0
	v_exp_f32_e32 v8, v86
	v_add_f32_e32 v0, v5, v0
	v_exp_f32_e32 v9, v87
	v_add_f32_e32 v0, v6, v0
	v_add_f32_e32 v0, v7, v0
	v_add3_u32 v86, s14, v147, v149
	v_add_f32_e32 v0, v8, v0
	v_add_u32_e32 v87, 0x2000, v86
	v_add_f32_e32 v0, v9, v0
	v_cvt_pk_bf16_f32 v2, v2, v3
	v_cvt_pk_bf16_f32 v3, v4, v5
	v_cvt_pk_bf16_f32 v4, v6, v7
	v_cvt_pk_bf16_f32 v5, v8, v9
	ds_read2_b64 v[6:9], v87 offset0:128 offset1:130
	ds_read2_b64 v[10:13], v87 offset0:132 offset1:134
	v_add_u32_e32 v86, 0x3000, v86
	s_waitcnt lgkmcnt(1)
	v_mfma_f32_32x32x16_bf16 v[32:47], v[6:9], v[2:5], v[32:47]
	ds_read2_b64 v[6:9], v86 offset0:160 offset1:162
	s_mul_i32 s1, s9, 0x4a00
	v_or_b32_e32 v184, s1, v131
	v_add_u32_e32 v185, v184, v133
	s_waitcnt vmcnt(3)
	ds_write_b128 v185, v[108:111]
	global_load_dwordx4 v[108:111], v180, s[10:11]
	v_exp_f32_e32 v14, v88
	v_exp_f32_e32 v15, v89
	v_exp_f32_e32 v80, v90
	v_exp_f32_e32 v81, v91
	v_exp_f32_e32 v82, v92
	v_exp_f32_e32 v83, v93
	s_waitcnt lgkmcnt(1)
	v_mfma_f32_32x32x16_bf16 v[16:31], v[6:9], v[2:5], v[16:31]
	ds_read2_b64 v[6:9], v86 offset0:164 offset1:166
	v_exp_f32_e32 v84, v94
	v_exp_f32_e32 v85, v95
	v_cvt_pk_bf16_f32 v2, v14, v15
	v_cvt_pk_bf16_f32 v3, v80, v81
	v_cvt_pk_bf16_f32 v4, v82, v83
	v_cvt_pk_bf16_f32 v5, v84, v85
	v_exp_f32_e32 v64, v64
	v_exp_f32_e32 v65, v65
	s_waitcnt lgkmcnt(0)
	v_mfma_f32_32x32x16_bf16 v[16:31], v[6:9], v[2:5], v[16:31]
	ds_read2_b64 v[6:9], v87 offset0:136 offset1:138
	v_add3_u32 v185, v184, v144, s33
	s_waitcnt vmcnt(2)
	ds_write2_b64 v185, v[104:105], v[106:107] offset1:1
	global_load_dwordx4 v[104:107], v182, s[16:17]
	v_exp_f32_e32 v66, v66
	v_exp_f32_e32 v67, v67
	v_exp_f32_e32 v68, v68
	v_exp_f32_e32 v69, v69
	v_exp_f32_e32 v70, v70
	v_exp_f32_e32 v71, v71
	v_mfma_f32_32x32x16_bf16 v[32:47], v[10:13], v[2:5], v[32:47]
	v_cvt_pk_bf16_f32 v2, v64, v65
	v_cvt_pk_bf16_f32 v3, v66, v67
	v_cvt_pk_bf16_f32 v4, v68, v69
	v_cvt_pk_bf16_f32 v5, v70, v71
	v_add_f32_e32 v0, v14, v0
	v_add_f32_e32 v0, v15, v0
	v_add_f32_e32 v0, v80, v0
	s_waitcnt lgkmcnt(1)
	v_mfma_f32_32x32x16_bf16 v[32:47], v[6:9], v[2:5], v[32:47]
	ds_read2_b64 v[6:9], v86 offset0:168 offset1:170
	v_add_u32_e32 v185, v184, v145
	s_waitcnt vmcnt(3)
	ds_write_b128 v185, v[112:115]
	global_load_dwordx4 v[112:115], v181, s[10:11]
	v_add_f32_e32 v0, v81, v0
	v_exp_f32_e32 v72, v72
	v_exp_f32_e32 v73, v73
	v_exp_f32_e32 v74, v74
	v_exp_f32_e32 v75, v75
	v_exp_f32_e32 v76, v76
	s_waitcnt lgkmcnt(1)
	v_mfma_f32_32x32x16_bf16 v[16:31], v[6:9], v[2:5], v[16:31]
	ds_read2_b64 v[6:9], v87 offset0:140 offset1:142
	v_exp_f32_e32 v77, v77
	v_exp_f32_e32 v78, v78
	v_exp_f32_e32 v79, v79
	v_add_f32_e32 v0, v82, v0
	v_add_f32_e32 v0, v83, v0
	v_add_f32_e32 v0, v84, v0
	v_add_f32_e32 v0, v85, v0
	v_cvt_pk_bf16_f32 v2, v72, v73
	v_cvt_pk_bf16_f32 v3, v74, v75
	v_cvt_pk_bf16_f32 v4, v76, v77
	v_cvt_pk_bf16_f32 v5, v78, v79
	v_add_f32_e32 v0, v64, v0
	v_add_f32_e32 v0, v65, v0
	s_waitcnt lgkmcnt(0)
	v_mfma_f32_32x32x16_bf16 v[32:47], v[6:9], v[2:5], v[32:47]
	ds_read2_b64 v[6:9], v86 offset0:172 offset1:174
	v_add3_u32 v185, v184, v146, s33
	s_waitcnt vmcnt(3)
	ds_write2_b64 v185, v[116:117], v[118:119] offset1:1
	global_load_dwordx4 v[116:119], v183, s[16:17]
	s_add_u32 s10, s10, 0x2000
	s_addc_u32 s11, s11, 0
	s_add_u32 s16, s16, 0x80
	s_addc_u32 s17, s17, 0
	v_add_f32_e32 v0, v66, v0
	v_add_f32_e32 v0, v67, v0
	v_add_f32_e32 v0, v68, v0
	v_add_f32_e32 v0, v69, v0
	v_add_f32_e32 v0, v70, v0
	v_add_f32_e32 v0, v71, v0
	v_add_f32_e32 v0, v72, v0
	v_add_f32_e32 v0, v73, v0
	s_waitcnt lgkmcnt(1)
	v_mfma_f32_32x32x16_bf16 v[16:31], v[6:9], v[2:5], v[16:31]
	v_add_f32_e32 v0, v74, v0
	v_add_f32_e32 v0, v75, v0
	v_add_f32_e32 v0, v76, v0
	v_add_f32_e32 v0, v77, v0
	v_add_f32_e32 v0, v78, v0
	v_add_f32_e32 v0, v79, v0
	v_add_f32_e32 v152, v152, v0
	v_cmp_lt_f32_e32 vcc, s20, v0
	s_cbranch_vccz .LBB0_707
	v_mov_b32_e32 v2, v0
	s_nop 1
	v_permlane32_swap_b32_e32 v0, v2
	v_add_f32_e32 v0, v0, v2
	v_log_f32_e32 v2, v0
	v_cmp_lt_f32_e32 vcc, s20, v0
	s_nop 1
	v_cndmask_b32_e32 v2, 0, v2, vcc
	v_exp_f32_e64 v0, -v2
	v_add_f32_e32 v153, v153, v2
	v_xor_b32_e32 v63, 0x80000000, v153
	v_mov_b32_e32 v62, v63
	v_mul_f32_e32 v152, v152, v0
	v_pk_mul_f32 v[46:47], v[46:47], v[0:1] op_sel_hi:[1,0]
	v_pk_mul_f32 v[44:45], v[44:45], v[0:1] op_sel_hi:[1,0]
	v_pk_mul_f32 v[42:43], v[42:43], v[0:1] op_sel_hi:[1,0]
	v_pk_mul_f32 v[40:41], v[40:41], v[0:1] op_sel_hi:[1,0]
	v_pk_mul_f32 v[38:39], v[38:39], v[0:1] op_sel_hi:[1,0]
	v_pk_mul_f32 v[36:37], v[36:37], v[0:1] op_sel_hi:[1,0]
	v_pk_mul_f32 v[34:35], v[34:35], v[0:1] op_sel_hi:[1,0]
	v_pk_mul_f32 v[32:33], v[32:33], v[0:1] op_sel_hi:[1,0]
	v_pk_mul_f32 v[30:31], v[30:31], v[0:1] op_sel_hi:[1,0]
	v_pk_mul_f32 v[28:29], v[28:29], v[0:1] op_sel_hi:[1,0]
	v_pk_mul_f32 v[26:27], v[26:27], v[0:1] op_sel_hi:[1,0]
	v_pk_mul_f32 v[24:25], v[24:25], v[0:1] op_sel_hi:[1,0]
	v_pk_mul_f32 v[22:23], v[22:23], v[0:1] op_sel_hi:[1,0]
	v_pk_mul_f32 v[20:21], v[20:21], v[0:1] op_sel_hi:[1,0]
	v_pk_mul_f32 v[18:19], v[18:19], v[0:1] op_sel_hi:[1,0]
	v_pk_mul_f32 v[16:17], v[16:17], v[0:1] op_sel_hi:[1,0]
	v_mov_b32_e32 v61, v63
	v_mov_b32_e32 v60, v63
	v_mov_b32_e32 v59, v63
	v_mov_b32_e32 v58, v63
	v_mov_b32_e32 v57, v63
	v_mov_b32_e32 v56, v63
	v_mov_b32_e32 v55, v63
	v_mov_b32_e32 v54, v63
	v_mov_b32_e32 v53, v63
	v_mov_b32_e32 v52, v63
	v_mov_b32_e32 v51, v63
	v_mov_b32_e32 v50, v63
	v_mov_b32_e32 v49, v63
	v_mov_b32_e32 v48, v63
	s_branch .LBB0_707

.LBB0_919:
	s_nop 7
	v_exp_f32_e32 v66, v66
	v_exp_f32_e32 v67, v67
	v_exp_f32_e32 v68, v68
	v_exp_f32_e32 v69, v69
	v_add_f32_e32 v147, 0, v66
	v_exp_f32_e32 v70, v70
	v_add_f32_e32 v147, v67, v147
	v_exp_f32_e32 v71, v71
	v_add_f32_e32 v147, v68, v147
	v_exp_f32_e32 v72, v72
	v_add_f32_e32 v147, v69, v147
	v_exp_f32_e32 v73, v73
	v_add_f32_e32 v147, v70, v147
	v_exp_f32_e32 v74, v74
	v_add_f32_e32 v147, v71, v147
	v_exp_f32_e32 v75, v75
	v_add_f32_e32 v147, v72, v147
	v_exp_f32_e32 v76, v76
	v_add_f32_e32 v147, v73, v147
	v_exp_f32_e32 v77, v77
	v_add_f32_e32 v147, v74, v147
	v_exp_f32_e32 v78, v78
	v_add_f32_e32 v147, v75, v147
	v_exp_f32_e32 v79, v79
	v_add_f32_e32 v147, v76, v147
	v_exp_f32_e32 v80, v80
	v_add_f32_e32 v147, v77, v147
	v_exp_f32_e32 v81, v81
	v_add_f32_e32 v147, v78, v147
	v_exp_f32_e32 v148, v50
	v_add_f32_e32 v147, v79, v147
	v_exp_f32_e32 v149, v51
	v_add_f32_e32 v50, v80, v147
	v_add_f32_e32 v50, v81, v50
	v_add3_u32 v153, s22, v181, v187
	v_add_f32_e32 v50, v148, v50
	v_add_u32_e32 v154, 0x2000, v153
	v_add_f32_e32 v147, v149, v50
	v_exp_f32_e32 v150, v52
	v_exp_f32_e32 v151, v53
	ds_read2_b64 v[50:53], v154 offset0:128 offset1:130
	v_add_u32_e32 v153, 0x3000, v153
	v_exp_f32_e32 v152, v54
	v_cvt_pk_bf16_f32 v54, v66, v67
	v_cvt_pk_bf16_f32 v66, v68, v69
	v_cvt_pk_bf16_f32 v67, v70, v71
	v_cvt_pk_bf16_f32 v68, v72, v73
	ds_read2_b64 v[70:73], v153 offset0:160 offset1:162
	v_cndmask_b32_e64 v69, 0, v68, s[0:1]
	v_cndmask_b32_e64 v68, 0, v67, s[0:1]
	v_cndmask_b32_e64 v67, 0, v66, s[0:1]
	v_cndmask_b32_e64 v66, 0, v54, s[0:1]
	v_exp_f32_e32 v155, v55
	v_exp_f32_e32 v193, v56
	s_waitcnt lgkmcnt(1)
	v_mfma_f32_32x32x16_bf16 v[18:33], v[50:53], v[66:69], v[18:33]
	s_mul_i32 s23, s17, 0x4a00
	v_or_b32_e32 v252, s23, v129
	v_add_u32_e32 v253, v252, v131
	s_waitcnt vmcnt(3)
	ds_write_b128 v253, v[98:101]
	global_load_dwordx4 v[98:101], v228, s[12:13]
	v_add_f32_e32 v50, v150, v147
	v_add_f32_e32 v50, v151, v50
	v_add_f32_e32 v147, v152, v50
	ds_read2_b64 v[50:53], v154 offset0:132 offset1:134
	v_exp_f32_e32 v194, v57
	v_cvt_pk_bf16_f32 v54, v74, v75
	v_cvt_pk_bf16_f32 v55, v76, v77
	s_waitcnt lgkmcnt(2)
	v_mfma_f32_32x32x16_bf16 v[2:17], v[70:73], v[66:69], v[2:17]
	ds_read2_b64 v[66:69], v153 offset0:164 offset1:166
	v_cvt_pk_bf16_f32 v56, v78, v79
	v_cvt_pk_bf16_f32 v57, v80, v81
	v_cndmask_b32_e64 v57, 0, v57, s[0:1]
	v_cndmask_b32_e64 v56, 0, v56, s[0:1]
	v_cndmask_b32_e64 v55, 0, v55, s[0:1]
	v_cndmask_b32_e64 v54, 0, v54, s[0:1]
	v_exp_f32_e32 v58, v58
	v_exp_f32_e32 v59, v59
	s_waitcnt lgkmcnt(1)
	v_mfma_f32_32x32x16_bf16 v[18:33], v[50:53], v[54:57], v[18:33]
	v_add3_u32 v253, v252, v185, s33
	s_waitcnt vmcnt(2)
	ds_write2_b64 v253, v[102:103], v[104:105] offset1:1
	global_load_dwordx4 v[102:105], v230, s[24:25]
	v_add_f32_e32 v50, v155, v147
	v_add_f32_e32 v50, v193, v50
	v_add_f32_e32 v50, v194, v50
	v_add_f32_e32 v70, v58, v50
	ds_read2_b64 v[50:53], v154 offset0:136 offset1:138
	v_exp_f32_e32 v60, v60
	v_exp_f32_e32 v71, v61
	s_waitcnt lgkmcnt(2)
	v_mfma_f32_32x32x16_bf16 v[2:17], v[66:69], v[54:57], v[2:17]
	ds_read2_b64 v[66:69], v153 offset0:168 offset1:170
	v_cvt_pk_bf16_f32 v54, v148, v149
	v_cvt_pk_bf16_f32 v55, v150, v151
	v_cvt_pk_bf16_f32 v56, v152, v155
	v_cvt_pk_bf16_f32 v57, v193, v194
	v_cndmask_b32_e64 v57, 0, v57, s[0:1]
	v_cndmask_b32_e64 v56, 0, v56, s[0:1]
	v_cndmask_b32_e64 v55, 0, v55, s[0:1]
	v_cndmask_b32_e64 v54, 0, v54, s[0:1]
	v_exp_f32_e32 v62, v62
	v_exp_f32_e32 v63, v63
	s_waitcnt lgkmcnt(1)
	v_mfma_f32_32x32x16_bf16 v[18:33], v[50:53], v[54:57], v[18:33]
	v_add_u32_e32 v253, v252, v180
	s_waitcnt vmcnt(3)
	ds_write_b128 v253, v[106:109]
	global_load_dwordx4 v[106:109], v229, s[12:13]
	v_add_f32_e32 v50, v59, v70
	v_add_f32_e32 v70, v60, v50
	ds_read2_b64 v[50:53], v154 offset0:140 offset1:142
	v_exp_f32_e32 v64, v64
	v_exp_f32_e32 v65, v65
	s_waitcnt lgkmcnt(2)
	v_mfma_f32_32x32x16_bf16 v[2:17], v[66:69], v[54:57], v[2:17]
	v_cvt_pk_bf16_f32 v54, v58, v59
	v_cvt_pk_bf16_f32 v55, v60, v71
	ds_read2_b64 v[58:61], v153 offset0:172 offset1:174
	v_cvt_pk_bf16_f32 v56, v62, v63
	v_cvt_pk_bf16_f32 v57, v64, v65
	v_cndmask_b32_e64 v57, 0, v57, s[0:1]
	v_cndmask_b32_e64 v56, 0, v56, s[0:1]
	v_cndmask_b32_e64 v55, 0, v55, s[0:1]
	v_cndmask_b32_e64 v54, 0, v54, s[0:1]
	s_waitcnt lgkmcnt(1)
	s_nop 0
	v_mfma_f32_32x32x16_bf16 v[18:33], v[50:53], v[54:57], v[18:33]
	v_add3_u32 v253, v252, v186, s33
	s_waitcnt vmcnt(3)
	ds_write2_b64 v253, v[110:111], v[112:113] offset1:1
	global_load_dwordx4 v[110:113], v231, s[24:25]
	s_add_u32 s12, s12, 0x2000
	s_addc_u32 s13, s13, 0
	s_add_u32 s24, s24, 0x80
	s_addc_u32 s25, s25, 0
	v_add_f32_e32 v50, v71, v70
	v_add_f32_e32 v50, v62, v50
	v_add_f32_e32 v50, v63, v50
	v_add_f32_e32 v50, v64, v50
	v_add_f32_e32 v50, v65, v50
	v_cndmask_b32_e64 v50, 0, v50, s[0:1]
	v_add_f32_e32 v133, v133, v50
	s_waitcnt lgkmcnt(1)
	v_mfma_f32_32x32x16_bf16 v[2:17], v[58:61], v[54:57], v[2:17]
	v_cmp_lt_f32_e32 vcc, s20, v50
	s_cbranch_vccz .LBB0_921
	v_mov_b32_e32 v34, v50
	s_nop 1
	v_permlane32_swap_b32_e32 v50, v34
	v_add_f32_e32 v34, v50, v34
	v_log_f32_e32 v35, v34
	v_cmp_lt_f32_e32 vcc, s20, v34
	s_nop 1
	v_cndmask_b32_e32 v35, 0, v35, vcc
	v_exp_f32_e64 v34, -v35
	v_add_f32_e32 v135, v135, v35
	v_xor_b32_e32 v49, 0x80000000, v135
	v_mov_b32_e32 v48, v49
	v_mul_f32_e32 v133, v133, v34
	v_pk_mul_f32 v[32:33], v[32:33], v[34:35] op_sel_hi:[1,0]
	v_pk_mul_f32 v[30:31], v[30:31], v[34:35] op_sel_hi:[1,0]
	v_pk_mul_f32 v[28:29], v[28:29], v[34:35] op_sel_hi:[1,0]
	v_pk_mul_f32 v[26:27], v[26:27], v[34:35] op_sel_hi:[1,0]
	v_pk_mul_f32 v[24:25], v[24:25], v[34:35] op_sel_hi:[1,0]
	v_pk_mul_f32 v[22:23], v[22:23], v[34:35] op_sel_hi:[1,0]
	v_pk_mul_f32 v[20:21], v[20:21], v[34:35] op_sel_hi:[1,0]
	v_pk_mul_f32 v[18:19], v[18:19], v[34:35] op_sel_hi:[1,0]
	v_pk_mul_f32 v[16:17], v[16:17], v[34:35] op_sel_hi:[1,0]
	v_pk_mul_f32 v[14:15], v[14:15], v[34:35] op_sel_hi:[1,0]
	v_pk_mul_f32 v[12:13], v[12:13], v[34:35] op_sel_hi:[1,0]
	v_pk_mul_f32 v[10:11], v[10:11], v[34:35] op_sel_hi:[1,0]
	v_pk_mul_f32 v[8:9], v[8:9], v[34:35] op_sel_hi:[1,0]
	v_pk_mul_f32 v[6:7], v[6:7], v[34:35] op_sel_hi:[1,0]
	v_pk_mul_f32 v[4:5], v[4:5], v[34:35] op_sel_hi:[1,0]
	v_pk_mul_f32 v[2:3], v[2:3], v[34:35] op_sel_hi:[1,0]
	v_mov_b32_e32 v47, v49
	v_mov_b32_e32 v46, v49
	v_mov_b32_e32 v45, v49
	v_mov_b32_e32 v44, v49
	v_mov_b32_e32 v43, v49
	v_mov_b32_e32 v42, v49
	v_mov_b32_e32 v41, v49
	v_mov_b32_e32 v40, v49
	v_mov_b32_e32 v39, v49
	v_mov_b32_e32 v38, v49
	v_mov_b32_e32 v37, v49
	v_mov_b32_e32 v36, v49
	v_mov_b32_e32 v35, v49
	v_mov_b32_e32 v34, v49
	s_branch .LBB0_921

.LBB0_936:
	s_nop 4
	v_exp_f32_e32 v66, v66
	v_exp_f32_e32 v67, v67
	v_exp_f32_e32 v68, v68
	v_exp_f32_e32 v69, v69
	v_add_f32_e32 v138, 0, v66
	v_exp_f32_e32 v70, v70
	v_add_f32_e32 v138, v67, v138
	v_exp_f32_e32 v71, v71
	v_add_f32_e32 v138, v68, v138
	v_exp_f32_e32 v72, v72
	v_add_f32_e32 v138, v69, v138
	v_exp_f32_e32 v73, v73
	v_add_f32_e32 v138, v70, v138
	v_exp_f32_e32 v74, v74
	v_add_f32_e32 v138, v71, v138
	v_exp_f32_e32 v75, v75
	v_add_f32_e32 v138, v72, v138
	v_exp_f32_e32 v76, v76
	v_add_f32_e32 v138, v73, v138
	v_exp_f32_e32 v77, v77
	v_add_f32_e32 v138, v74, v138
	v_exp_f32_e32 v78, v78
	v_add_f32_e32 v138, v75, v138
	v_exp_f32_e32 v79, v79
	v_add_f32_e32 v138, v76, v138
	v_exp_f32_e32 v80, v80
	v_add_f32_e32 v138, v77, v138
	v_exp_f32_e32 v81, v81
	v_add_f32_e32 v138, v78, v138
	v_exp_f32_e32 v139, v50
	v_add_f32_e32 v138, v79, v138
	v_add_f32_e32 v138, v80, v138
	v_add_f32_e32 v138, v81, v138
	v_add_f32_e32 v50, v139, v138
	v_exp_f32_e32 v138, v52
	v_cvt_pk_bf16_f32 v52, v66, v67
	v_add3_u32 v66, s16, v181, v187
	v_add_u32_e32 v67, 0x2000, v66
	v_exp_f32_e32 v143, v56
	v_exp_f32_e32 v144, v57
	v_exp_f32_e32 v145, v58
	v_exp_f32_e32 v147, v59
	v_exp_f32_e32 v148, v60
	v_exp_f32_e32 v149, v61
	v_exp_f32_e32 v150, v62
	v_exp_f32_e32 v151, v63
	ds_read2_b64 v[56:59], v67 offset0:128 offset1:130
	ds_read2_b64 v[60:63], v67 offset0:132 offset1:134
	v_exp_f32_e32 v140, v53
	v_exp_f32_e32 v141, v54
	v_exp_f32_e32 v142, v55
	v_cvt_pk_bf16_f32 v53, v68, v69
	v_cvt_pk_bf16_f32 v54, v70, v71
	v_cvt_pk_bf16_f32 v55, v72, v73
	v_add_u32_e32 v66, 0x3000, v66
	v_exp_f32_e32 v51, v51
	s_waitcnt lgkmcnt(1)
	v_mfma_f32_32x32x16_bf16 v[18:33], v[56:59], v[52:55], v[18:33]
	ds_read2_b64 v[56:59], v66 offset0:160 offset1:162
	s_mul_i32 s22, s15, 0x4a00
	v_or_b32_e32 v252, s22, v129
	v_add_u32_e32 v253, v252, v131
	s_waitcnt vmcnt(3)
	ds_write_b128 v253, v[98:101]
	global_load_dwordx4 v[98:101], v228, s[12:13]
	v_exp_f32_e32 v64, v64
	v_exp_f32_e32 v65, v65
	v_add_f32_e32 v50, v51, v50
	v_add_f32_e32 v50, v138, v50
	v_add_f32_e32 v50, v140, v50
	v_add_f32_e32 v50, v141, v50
	s_waitcnt lgkmcnt(1)
	v_mfma_f32_32x32x16_bf16 v[2:17], v[56:59], v[52:55], v[2:17]
	ds_read2_b64 v[56:59], v66 offset0:164 offset1:166
	v_cvt_pk_bf16_f32 v52, v74, v75
	v_cvt_pk_bf16_f32 v53, v76, v77
	v_cvt_pk_bf16_f32 v54, v78, v79
	v_cvt_pk_bf16_f32 v55, v80, v81
	v_add_f32_e32 v50, v142, v50
	v_add_f32_e32 v50, v143, v50
	s_waitcnt lgkmcnt(0)
	v_mfma_f32_32x32x16_bf16 v[2:17], v[56:59], v[52:55], v[2:17]
	ds_read2_b64 v[56:59], v67 offset0:136 offset1:138
	v_add3_u32 v253, v252, v185, s33
	s_waitcnt vmcnt(2)
	ds_write2_b64 v253, v[102:103], v[104:105] offset1:1
	global_load_dwordx4 v[102:105], v230, s[24:25]
	v_add_f32_e32 v50, v144, v50
	v_add_f32_e32 v50, v145, v50
	v_add_f32_e32 v50, v147, v50
	v_add_f32_e32 v50, v148, v50
	v_add_f32_e32 v50, v149, v50
	v_add_f32_e32 v50, v150, v50
	v_mfma_f32_32x32x16_bf16 v[18:33], v[60:63], v[52:55], v[18:33]
	v_cvt_pk_bf16_f32 v52, v139, v51
	v_cvt_pk_bf16_f32 v53, v138, v140
	v_cvt_pk_bf16_f32 v54, v141, v142
	v_cvt_pk_bf16_f32 v55, v143, v144
	v_add_f32_e32 v50, v151, v50
	v_add_f32_e32 v50, v64, v50
	v_add_f32_e32 v50, v65, v50
	s_waitcnt lgkmcnt(1)
	v_mfma_f32_32x32x16_bf16 v[18:33], v[56:59], v[52:55], v[18:33]
	ds_read2_b64 v[56:59], v66 offset0:168 offset1:170
	v_add_u32_e32 v253, v252, v180
	s_waitcnt vmcnt(3)
	ds_write_b128 v253, v[106:109]
	global_load_dwordx4 v[106:109], v229, s[12:13]
	v_add_f32_e32 v136, v136, v50
	v_cmp_lt_f32_e32 vcc, s20, v50
	s_waitcnt lgkmcnt(1)
	v_mfma_f32_32x32x16_bf16 v[2:17], v[56:59], v[52:55], v[2:17]
	ds_read2_b64 v[56:59], v67 offset0:140 offset1:142
	v_cvt_pk_bf16_f32 v52, v145, v147
	v_cvt_pk_bf16_f32 v53, v148, v149
	v_cvt_pk_bf16_f32 v54, v150, v151
	v_cvt_pk_bf16_f32 v55, v64, v65
	s_waitcnt lgkmcnt(0)
	s_nop 0
	v_mfma_f32_32x32x16_bf16 v[18:33], v[56:59], v[52:55], v[18:33]
	ds_read2_b64 v[56:59], v66 offset0:172 offset1:174
	v_add3_u32 v253, v252, v186, s33
	s_waitcnt vmcnt(3)
	ds_write2_b64 v253, v[110:111], v[112:113] offset1:1
	global_load_dwordx4 v[110:113], v231, s[24:25]
	s_add_u32 s12, s12, 0x2000
	s_addc_u32 s13, s13, 0
	s_add_u32 s24, s24, 0x80
	s_addc_u32 s25, s25, 0
	s_waitcnt lgkmcnt(1)
	v_mfma_f32_32x32x16_bf16 v[2:17], v[56:59], v[52:55], v[2:17]
	s_cbranch_vccz .LBB0_938
	v_mov_b32_e32 v34, v50
	s_nop 1
	v_permlane32_swap_b32_e32 v50, v34
	v_add_f32_e32 v34, v50, v34
	v_log_f32_e32 v35, v34
	v_cmp_lt_f32_e32 vcc, s20, v34
	s_nop 1
	v_cndmask_b32_e32 v35, 0, v35, vcc
	v_exp_f32_e64 v34, -v35
	v_add_f32_e32 v0, v0, v35
	v_xor_b32_e32 v49, 0x80000000, v0
	v_mov_b32_e32 v48, v49
	v_mul_f32_e32 v136, v136, v34
	v_pk_mul_f32 v[32:33], v[32:33], v[34:35] op_sel_hi:[1,0]
	v_pk_mul_f32 v[30:31], v[30:31], v[34:35] op_sel_hi:[1,0]
	v_pk_mul_f32 v[28:29], v[28:29], v[34:35] op_sel_hi:[1,0]
	v_pk_mul_f32 v[26:27], v[26:27], v[34:35] op_sel_hi:[1,0]
	v_pk_mul_f32 v[24:25], v[24:25], v[34:35] op_sel_hi:[1,0]
	v_pk_mul_f32 v[22:23], v[22:23], v[34:35] op_sel_hi:[1,0]
	v_pk_mul_f32 v[20:21], v[20:21], v[34:35] op_sel_hi:[1,0]
	v_pk_mul_f32 v[18:19], v[18:19], v[34:35] op_sel_hi:[1,0]
	v_pk_mul_f32 v[16:17], v[16:17], v[34:35] op_sel_hi:[1,0]
	v_pk_mul_f32 v[14:15], v[14:15], v[34:35] op_sel_hi:[1,0]
	v_pk_mul_f32 v[12:13], v[12:13], v[34:35] op_sel_hi:[1,0]
	v_pk_mul_f32 v[10:11], v[10:11], v[34:35] op_sel_hi:[1,0]
	v_pk_mul_f32 v[8:9], v[8:9], v[34:35] op_sel_hi:[1,0]
	v_pk_mul_f32 v[6:7], v[6:7], v[34:35] op_sel_hi:[1,0]
	v_pk_mul_f32 v[4:5], v[4:5], v[34:35] op_sel_hi:[1,0]
	v_pk_mul_f32 v[2:3], v[2:3], v[34:35] op_sel_hi:[1,0]
	v_mov_b32_e32 v47, v49
	v_mov_b32_e32 v46, v49
	v_mov_b32_e32 v45, v49
	v_mov_b32_e32 v44, v49
	v_mov_b32_e32 v43, v49
	v_mov_b32_e32 v42, v49
	v_mov_b32_e32 v41, v49
	v_mov_b32_e32 v40, v49
	v_mov_b32_e32 v39, v49
	v_mov_b32_e32 v38, v49
	v_mov_b32_e32 v37, v49
	v_mov_b32_e32 v36, v49
	v_mov_b32_e32 v35, v49
	v_mov_b32_e32 v34, v49
	s_branch .LBB0_938
